# attention unmasked tiles: 32-key half tiles software-pipelined inside each wave (softmax of half 0 under QK of half 1, softmax of half 1 under PV)
# speedup vs baseline: 1.0146x; 1.0016x over previous
; DI int crow(int reg, int hh) { return (reg & 3) + 8 * (reg >> 2) + 4 * hh; }
; #define ATT_RD(dst, off) asm volatile("ds_read_b128 %0, %1 offset:" #off : "=&v"(dst) : "v"(kaddr) : "memory")
; __device__ __forceinline__ void attn_phase(LAS unsigned char* ldsb, bf16_t* P, const bf16_t* Kn, const bf16_t* KPE, const bf16_t* VT) {
;     ...
;                 if (k0 <= q0 + w * 32 + 31) {
;                     f32x16 st[2];
; #pragma unroll
;                     for (int kb = 0; kb < 2; ++kb) for (int i = 0; i < 16; ++i) st[kb][i] = 0.f;
;                     {
;                         const unsigned kaddr = (unsigned)(size_t)(sK + r * 200 + hh * 8);
;                         bf16x8 ka0, ka1, kb0, kb1;
;     ...
;                         ATT_RD(ka0, 0);   ATT_RD(ka1, 12800);
;                         ATT_RD(kb0, 32);  ATT_RD(kb1, 12832);  ATT_WT(2, ka0, ka1); ATT_MM(ka0, ka1, 0);
;                         ATT_RD(ka0, 64);  ATT_RD(ka1, 12864);  ATT_WT(2, kb0, kb1); ATT_MM(kb0, kb1, 1);
;                         ATT_RD(kb0, 96);  ATT_RD(kb1, 12896);  ATT_WT(2, ka0, ka1); ATT_MM(ka0, ka1, 2);
;                         ATT_RD(ka0, 128); ATT_RD(ka1, 12928);  ATT_WT(2, kb0, kb1); ATT_MM(kb0, kb1, 3);
;                         ATT_RD(kb0, 160); ATT_RD(kb1, 12960);  ATT_WT(2, ka0, ka1); ATT_MM(ka0, ka1, 4);
;                         ATT_RD(ka0, 192); ATT_RD(ka1, 12992);  ATT_WT(2, kb0, kb1); ATT_MM(kb0, kb1, 5);
;                         ATT_RD(kb0, 224); ATT_RD(kb1, 13024);  ATT_WT(2, ka0, ka1); ATT_MM(ka0, ka1, 6);
;                         ATT_RD(ka0, 256); ATT_RD(ka1, 13056);  ATT_WT(2, kb0, kb1); ATT_MM(kb0, kb1, 7);
;                         ATT_RD(kb0, 288); ATT_RD(kb1, 13088);  ATT_WT(2, ka0, ka1); ATT_MM(ka0, ka1, 8);
;                         ATT_RD(ka0, 320); ATT_RD(ka1, 13120);  ATT_WT(2, kb0, kb1); ATT_MM(kb0, kb1, 9);
;                         ATT_RD(kb0, 352); ATT_RD(kb1, 13152);  ATT_WT(2, ka0, ka1); ATT_MM(ka0, ka1, 10);
;                         ATT_WT(0, kb0, kb1); ATT_MM(kb0, kb1, 11);
;     ...
;                     }
;                     if (k0 + 63 > q0 + w * 32) {
; #pragma unroll
;                         for (int kb = 0; kb < 2; ++kb)
; #pragma unroll
;                             for (int i = 0; i < 16; ++i) { const int key = k0 + kb * 32 + crow(i, hh); if (key > qabs) st[kb][i] = -INFINITY; }
;                     }
.Lattn_nopre:
	s_sub_i32 s12, s78, 63
	s_cmp_gt_i32 s12, s76
	s_cbranch_scc1 .LBB0_1526
	s_cmp_le_i32 s78, s45
	s_cbranch_scc1 .Lattn_fast
	ds_read_b128 v[2:5], v241 offset:0
	ds_read_b128 v[6:9], v241 offset:12800
	ds_read_b128 v[10:13], v241 offset:32
	ds_read_b128 v[154:157], v241 offset:12832
	ds_read_b128 v[158:161], v241 offset:64
	ds_read_b128 v[162:165], v241 offset:12864
	ds_read_b128 v[166:169], v241 offset:96
	ds_read_b128 v[170:173], v241 offset:12896
	s_cmp_le_i32 s78, s45
	s_waitcnt lgkmcnt(6)
	v_mfma_f32_32x32x16_bf16 v[96:111], v[2:5], v[220:223], 0
	ds_read_b128 v[2:5], v241 offset:128
	v_mfma_f32_32x32x16_bf16 v[80:95], v[6:9], v[220:223], 0
	ds_read_b128 v[6:9], v241 offset:12928
	s_waitcnt lgkmcnt(6)
	v_mfma_f32_32x32x16_bf16 v[96:111], v[10:13], v[216:219], v[96:111]
	ds_read_b128 v[10:13], v241 offset:160
	v_mfma_f32_32x32x16_bf16 v[80:95], v[154:157], v[216:219], v[80:95]
	ds_read_b128 v[154:157], v241 offset:12960
	s_waitcnt lgkmcnt(6)
	v_mfma_f32_32x32x16_bf16 v[96:111], v[158:161], v[212:215], v[96:111]
	ds_read_b128 v[158:161], v241 offset:192
	v_mfma_f32_32x32x16_bf16 v[80:95], v[162:165], v[212:215], v[80:95]
	ds_read_b128 v[162:165], v241 offset:12992
	s_waitcnt lgkmcnt(6)
	v_mfma_f32_32x32x16_bf16 v[96:111], v[166:169], v[208:211], v[96:111]
	ds_read_b128 v[166:169], v241 offset:224
	v_mfma_f32_32x32x16_bf16 v[80:95], v[170:173], v[208:211], v[80:95]
	ds_read_b128 v[170:173], v241 offset:13024
	s_waitcnt lgkmcnt(6)
	v_mfma_f32_32x32x16_bf16 v[96:111], v[2:5], v[204:207], v[96:111]
	ds_read_b128 v[2:5], v241 offset:256
	v_mfma_f32_32x32x16_bf16 v[80:95], v[6:9], v[204:207], v[80:95]
	ds_read_b128 v[6:9], v241 offset:13056
	s_waitcnt lgkmcnt(6)
	v_mfma_f32_32x32x16_bf16 v[96:111], v[10:13], v[200:203], v[96:111]
	ds_read_b128 v[10:13], v241 offset:288
	v_mfma_f32_32x32x16_bf16 v[80:95], v[154:157], v[200:203], v[80:95]
	ds_read_b128 v[154:157], v241 offset:13088
	s_waitcnt lgkmcnt(6)
	v_mfma_f32_32x32x16_bf16 v[96:111], v[158:161], v[196:199], v[96:111]
	ds_read_b128 v[158:161], v241 offset:320
	v_mfma_f32_32x32x16_bf16 v[80:95], v[162:165], v[196:199], v[80:95]
	ds_read_b128 v[162:165], v241 offset:13120
	s_waitcnt lgkmcnt(6)
	v_mfma_f32_32x32x16_bf16 v[96:111], v[166:169], v[192:195], v[96:111]
	ds_read_b128 v[166:169], v241 offset:352
	v_mfma_f32_32x32x16_bf16 v[80:95], v[170:173], v[192:195], v[80:95]
	ds_read_b128 v[170:173], v241 offset:13152
	s_waitcnt lgkmcnt(6)
	v_mfma_f32_32x32x16_bf16 v[96:111], v[2:5], v[188:191], v[96:111]
	v_mfma_f32_32x32x16_bf16 v[80:95], v[6:9], v[188:191], v[80:95]
	s_waitcnt lgkmcnt(4)
	v_mfma_f32_32x32x16_bf16 v[96:111], v[10:13], v[184:187], v[96:111]
	v_mfma_f32_32x32x16_bf16 v[80:95], v[154:157], v[184:187], v[80:95]
	s_waitcnt lgkmcnt(2)
	v_mfma_f32_32x32x16_bf16 v[96:111], v[158:161], v[180:183], v[96:111]
	v_mfma_f32_32x32x16_bf16 v[80:95], v[162:165], v[180:183], v[80:95]
	s_waitcnt lgkmcnt(0)
	v_mfma_f32_32x32x16_bf16 v[96:111], v[166:169], v[176:179], v[96:111]
	v_mfma_f32_32x32x16_bf16 v[80:95], v[170:173], v[176:179], v[80:95]
	s_cbranch_scc1 .LBB0_1530
	v_add_u32_e32 v0, s78, v229
	v_subrev_u32_e32 v2, 63, v0
	v_cmp_gt_i32_e32 vcc, v2, v228
	s_nop 6
	v_cndmask_b32_e32 v3, v96, v233, vcc
	v_cmp_lt_i32_e32 vcc, v2, v228
	v_subrev_u32_e32 v2, 61, v0
	s_nop 0
	v_cndmask_b32_e32 v96, v3, v96, vcc
	v_cndmask_b32_e32 v97, v233, v97, vcc
	v_cmp_le_i32_e32 vcc, v2, v228
	v_subrev_u32_e32 v2, 60, v0
	s_nop 0
	v_cndmask_b32_e32 v98, v233, v98, vcc
	v_cmp_le_i32_e32 vcc, v2, v228
	v_subrev_u32_e32 v2, 55, v0
	s_nop 0
	v_cndmask_b32_e32 v99, v233, v99, vcc
	v_cmp_le_i32_e32 vcc, v2, v228
	v_subrev_u32_e32 v2, 54, v0
	s_nop 0
	v_cndmask_b32_e32 v100, v233, v100, vcc
	v_cmp_le_i32_e32 vcc, v2, v228
	v_subrev_u32_e32 v2, 53, v0
	s_nop 0
	v_cndmask_b32_e32 v101, v233, v101, vcc
	v_cmp_le_i32_e32 vcc, v2, v228
	v_subrev_u32_e32 v2, 52, v0
	s_nop 0
	v_cndmask_b32_e32 v102, v233, v102, vcc
	v_cmp_le_i32_e32 vcc, v2, v228
	v_subrev_u32_e32 v2, 47, v0
	s_nop 0
	v_cndmask_b32_e32 v103, v233, v103, vcc
	v_cmp_le_i32_e32 vcc, v2, v228
	v_subrev_u32_e32 v2, 46, v0
	s_nop 0
	v_cndmask_b32_e32 v104, v233, v104, vcc
	v_cmp_le_i32_e32 vcc, v2, v228
	v_subrev_u32_e32 v2, 45, v0
	s_nop 0
	v_cndmask_b32_e32 v105, v233, v105, vcc
	v_cmp_le_i32_e32 vcc, v2, v228
	v_subrev_u32_e32 v2, 44, v0
	s_nop 0
	v_cndmask_b32_e32 v106, v233, v106, vcc
	v_cmp_le_i32_e32 vcc, v2, v228
	v_subrev_u32_e32 v2, 39, v0
	s_nop 0
	v_cndmask_b32_e32 v107, v233, v107, vcc
	v_cmp_le_i32_e32 vcc, v2, v228
	v_subrev_u32_e32 v2, 38, v0
	s_nop 0
	v_cndmask_b32_e32 v108, v233, v108, vcc
	v_cmp_le_i32_e32 vcc, v2, v228
	v_subrev_u32_e32 v2, 37, v0
	s_nop 0
	v_cndmask_b32_e32 v109, v233, v109, vcc
	v_cmp_le_i32_e32 vcc, v2, v228
	v_subrev_u32_e32 v2, 36, v0
	s_nop 0
	v_cndmask_b32_e32 v110, v233, v110, vcc
	v_cmp_le_i32_e32 vcc, v2, v228
	v_subrev_u32_e32 v2, 31, v0
	s_nop 0
	v_cndmask_b32_e32 v111, v233, v111, vcc
	v_cmp_le_i32_e32 vcc, v2, v228
	v_subrev_u32_e32 v2, 30, v0
	s_nop 0
	v_cndmask_b32_e32 v80, v233, v80, vcc
	v_cmp_le_i32_e32 vcc, v2, v228
	v_subrev_u32_e32 v2, 29, v0
	s_nop 0
	v_cndmask_b32_e32 v81, v233, v81, vcc
	v_cmp_le_i32_e32 vcc, v2, v228
	v_subrev_u32_e32 v2, 28, v0
	s_nop 0
	v_cndmask_b32_e32 v82, v233, v82, vcc
	v_cmp_le_i32_e32 vcc, v2, v228
	v_subrev_u32_e32 v2, 23, v0
	s_nop 0
	v_cndmask_b32_e32 v83, v233, v83, vcc
	v_cmp_le_i32_e32 vcc, v2, v228
	v_subrev_u32_e32 v2, 22, v0
	s_nop 0
	v_cndmask_b32_e32 v84, v233, v84, vcc
	v_cmp_le_i32_e32 vcc, v2, v228
	v_subrev_u32_e32 v2, 21, v0
	s_nop 0
	v_cndmask_b32_e32 v85, v233, v85, vcc
	v_cmp_le_i32_e32 vcc, v2, v228
	v_subrev_u32_e32 v2, 20, v0
	s_nop 0
	v_cndmask_b32_e32 v86, v233, v86, vcc
	v_cmp_le_i32_e32 vcc, v2, v228
	v_add_u32_e32 v2, -15, v0
	s_nop 0
	v_cndmask_b32_e32 v87, v233, v87, vcc
	v_cmp_le_i32_e32 vcc, v2, v228
	v_add_u32_e32 v2, -14, v0
	s_nop 0
	v_cndmask_b32_e32 v88, v233, v88, vcc
	v_cmp_le_i32_e32 vcc, v2, v228
	v_add_u32_e32 v2, -13, v0
	s_nop 0
	v_cndmask_b32_e32 v89, v233, v89, vcc
	v_cmp_le_i32_e32 vcc, v2, v228
	v_add_u32_e32 v2, -12, v0
	s_nop 0
	v_cndmask_b32_e32 v90, v233, v90, vcc
	v_cmp_le_i32_e32 vcc, v2, v228
	v_add_u32_e32 v2, -7, v0
	s_nop 0
	v_cndmask_b32_e32 v91, v233, v91, vcc
	v_cmp_le_i32_e32 vcc, v2, v228
	v_add_u32_e32 v2, -6, v0
	s_nop 0
	v_cndmask_b32_e32 v92, v233, v92, vcc
	v_cmp_le_i32_e32 vcc, v2, v228
	v_add_u32_e32 v2, -5, v0
	v_add_u32_e32 v0, -4, v0
	v_cndmask_b32_e32 v93, v233, v93, vcc
	v_cmp_le_i32_e32 vcc, v2, v228
	s_nop 1
	v_cndmask_b32_e32 v94, v233, v94, vcc
	v_cmp_le_i32_e32 vcc, v0, v228
	s_nop 1
	v_cndmask_b32_e32 v95, v233, v95, vcc

; __device__ __forceinline__ void attn_phase(LAS unsigned char* ldsb, bf16_t* P, const bf16_t* Kn, const bf16_t* KPE, const bf16_t* VT) {
;     ...
;                         ATT_RD(ka0, 0);   ATT_RD(ka1, 12800);
;                         ATT_RD(kb0, 32);  ATT_RD(kb1, 12832);  ATT_WT(2, ka0, ka1); ATT_MM(ka0, ka1, 0);
;                         ATT_RD(ka0, 64);  ATT_RD(ka1, 12864);  ATT_WT(2, kb0, kb1); ATT_MM(kb0, kb1, 1);
;                         ATT_RD(kb0, 96);  ATT_RD(kb1, 12896);  ATT_WT(2, ka0, ka1); ATT_MM(ka0, ka1, 2);
;                         ATT_RD(ka0, 128); ATT_RD(ka1, 12928);  ATT_WT(2, kb0, kb1); ATT_MM(kb0, kb1, 3);
;                         ATT_RD(kb0, 160); ATT_RD(kb1, 12960);  ATT_WT(2, ka0, ka1); ATT_MM(ka0, ka1, 4);
;                         ATT_RD(ka0, 192); ATT_RD(ka1, 12992);  ATT_WT(2, kb0, kb1); ATT_MM(kb0, kb1, 5);
;                         ATT_RD(kb0, 224); ATT_RD(kb1, 13024);  ATT_WT(2, ka0, ka1); ATT_MM(ka0, ka1, 6);
;                         ATT_RD(ka0, 256); ATT_RD(ka1, 13056);  ATT_WT(2, kb0, kb1); ATT_MM(kb0, kb1, 7);
;                         ATT_RD(kb0, 288); ATT_RD(kb1, 13088);  ATT_WT(2, ka0, ka1); ATT_MM(ka0, ka1, 8);
;                         ATT_RD(ka0, 320); ATT_RD(ka1, 13120);  ATT_WT(2, kb0, kb1); ATT_MM(kb0, kb1, 9);
;                         ATT_RD(kb0, 352); ATT_RD(kb1, 13152);  ATT_WT(2, ka0, ka1); ATT_MM(ka0, ka1, 10);
;                         ATT_WT(0, kb0, kb1); ATT_MM(kb0, kb1, 11);
;     ...
;                     }
;                     if (k0 + 63 > q0 + w * 32) {
; #pragma unroll
;                         for (int kb = 0; kb < 2; ++kb)
; #pragma unroll
;                             for (int i = 0; i < 16; ++i) { const int key = k0 + kb * 32 + crow(i, hh); if (key > qabs) st[kb][i] = -INFINITY; }
;                     }
;                     float mx = st[0][0];
; #pragma unroll
;                     for (int kb = 0; kb < 2; ++kb)
; #pragma unroll
;                         for (int i = 0; i < 16; ++i) mx = fmaxf(mx, st[kb][i]);
;                     mx = fmaxf(mx, __shfl_xor(mx, 32));
;                     if (__builtin_amdgcn_ballot_w64(mx > mrun) != 0ull) {
;                         const float mnew = fmaxf(mrun, mx);
;                         const float alpha = __builtin_amdgcn_exp2f(mrun - mnew);
;                         mrun = mnew; lrun *= alpha;
; #pragma unroll
.Lattn_fast:
	ds_read_b128 v[154:157], v241 offset:0
	ds_read_b128 v[158:161], v241 offset:32
	ds_read_b128 v[162:165], v241 offset:64
	ds_read_b128 v[166:169], v241 offset:96
	ds_read_b128 v[170:173], v241 offset:128
	ds_read_b128 v[244:247], v241 offset:160
	s_waitcnt lgkmcnt(5)
	v_mfma_f32_32x32x16_bf16 v[96:111], v[154:157], v[220:223], 0
	ds_read_b128 v[248:251], v241 offset:192
	s_waitcnt lgkmcnt(5)
	v_mfma_f32_32x32x16_bf16 v[96:111], v[158:161], v[216:219], v[96:111]
	ds_read_b128 v[252:255], v241 offset:224
	s_waitcnt lgkmcnt(5)
	v_mfma_f32_32x32x16_bf16 v[96:111], v[162:165], v[212:215], v[96:111]
	ds_read_b128 v[154:157], v241 offset:256
	s_waitcnt lgkmcnt(5)
	v_mfma_f32_32x32x16_bf16 v[96:111], v[166:169], v[208:211], v[96:111]
	ds_read_b128 v[158:161], v241 offset:288
	s_waitcnt lgkmcnt(5)
	v_mfma_f32_32x32x16_bf16 v[96:111], v[170:173], v[204:207], v[96:111]
	ds_read_b128 v[162:165], v241 offset:320
	s_waitcnt lgkmcnt(5)
	v_mfma_f32_32x32x16_bf16 v[96:111], v[244:247], v[200:203], v[96:111]
	ds_read_b128 v[166:169], v241 offset:352
	s_waitcnt lgkmcnt(5)
	v_mfma_f32_32x32x16_bf16 v[96:111], v[248:251], v[196:199], v[96:111]
	ds_read_b128 v[170:173], v241 offset:12800
	s_waitcnt lgkmcnt(5)
	v_mfma_f32_32x32x16_bf16 v[96:111], v[252:255], v[192:195], v[96:111]
	ds_read_b128 v[244:247], v241 offset:12832
	s_waitcnt lgkmcnt(5)
	v_mfma_f32_32x32x16_bf16 v[96:111], v[154:157], v[188:191], v[96:111]
	ds_read_b128 v[248:251], v241 offset:12864
	s_waitcnt lgkmcnt(5)
	v_mfma_f32_32x32x16_bf16 v[96:111], v[158:161], v[184:187], v[96:111]
	ds_read_b128 v[252:255], v241 offset:12896
	s_waitcnt lgkmcnt(5)
	v_mfma_f32_32x32x16_bf16 v[96:111], v[162:165], v[180:183], v[96:111]
	ds_read_b128 v[154:157], v241 offset:12928
	s_waitcnt lgkmcnt(5)
	v_mfma_f32_32x32x16_bf16 v[96:111], v[166:169], v[176:179], v[96:111]
	ds_read_b128 v[158:161], v241 offset:12960
	s_waitcnt lgkmcnt(5)
	v_mfma_f32_32x32x16_bf16 v[80:95], v[170:173], v[220:223], 0
	ds_read_b128 v[162:165], v241 offset:12992
	s_waitcnt lgkmcnt(5)
	v_mfma_f32_32x32x16_bf16 v[80:95], v[244:247], v[216:219], v[80:95]
	ds_read_b128 v[166:169], v241 offset:13024
	s_waitcnt lgkmcnt(5)
	v_mfma_f32_32x32x16_bf16 v[80:95], v[248:251], v[212:215], v[80:95]
	ds_read_b128 v[170:173], v241 offset:13056
	s_waitcnt lgkmcnt(5)
	v_mfma_f32_32x32x16_bf16 v[80:95], v[252:255], v[208:211], v[80:95]
	ds_read_b128 v[244:247], v241 offset:13088
	s_waitcnt lgkmcnt(5)
	v_mfma_f32_32x32x16_bf16 v[80:95], v[154:157], v[204:207], v[80:95]
	ds_read_b128 v[248:251], v241 offset:13120
	v_max_f32_e32 v14, v97, v97
	v_max_f32_e32 v15, v96, v96
	v_max_f32_e32 v14, v15, v14
	v_max3_f32 v14, v14, v98, v99
	v_max3_f32 v14, v14, v100, v101
	v_max3_f32 v14, v14, v102, v103
	v_max3_f32 v14, v14, v104, v105
	s_waitcnt lgkmcnt(5)
	v_mfma_f32_32x32x16_bf16 v[80:95], v[158:161], v[200:203], v[80:95]
	ds_read_b128 v[252:255], v241 offset:13152
	v_max3_f32 v14, v14, v106, v107
	v_max3_f32 v14, v14, v108, v109
	v_max3_f32 v14, v14, v110, v111
	v_sub_f32_e32 v15, v14, v240
	v_cmp_lt_f32_e32 vcc, 4.0, v15
	s_cbranch_vccnz .Lf_rare0
.Lf_back0:
	v_sub_f32_e32 v96, v96, v240
	v_sub_f32_e32 v97, v97, v240
	v_exp_f32_e32 v96, v96
	s_waitcnt lgkmcnt(5)
	v_mfma_f32_32x32x16_bf16 v[80:95], v[162:165], v[196:199], v[80:95]
	ds_read2_b64 v[154:157], v239 offset0:0 offset1:2
	v_sub_f32_e32 v98, v98, v240
	v_exp_f32_e32 v97, v97
	v_sub_f32_e32 v99, v99, v240
	v_exp_f32_e32 v98, v98
	v_add_f32_e32 v0, 0, v96
	v_exp_f32_e32 v99, v99
	v_sub_f32_e32 v100, v100, v240
	s_waitcnt lgkmcnt(5)
	v_mfma_f32_32x32x16_bf16 v[80:95], v[166:169], v[192:195], v[80:95]
	ds_read2_b64 v[158:161], v238 offset0:0 offset1:2
	v_add_f32_e32 v0, v97, v0
	v_sub_f32_e32 v101, v101, v240
	v_exp_f32_e32 v100, v100
	v_cvt_pk_bf16_f32 v2, v96, v97
	v_add_f32_e32 v0, v98, v0
	v_exp_f32_e32 v101, v101
	v_sub_f32_e32 v102, v102, v240
	s_waitcnt lgkmcnt(5)
	v_mfma_f32_32x32x16_bf16 v[80:95], v[170:173], v[188:191], v[80:95]
	ds_read2_b64 v[162:165], v237 offset0:0 offset1:2
	v_add_f32_e32 v0, v99, v0
	v_sub_f32_e32 v103, v103, v240
	v_exp_f32_e32 v102, v102
	v_cvt_pk_bf16_f32 v3, v98, v99
	v_exp_f32_e32 v103, v103
	v_add_f32_e32 v0, v100, v0
	v_add_f32_e32 v0, v101, v0
	s_waitcnt lgkmcnt(5)
	v_mfma_f32_32x32x16_bf16 v[80:95], v[244:247], v[184:187], v[80:95]
	ds_read2_b64 v[166:169], v235 offset0:0 offset1:2
	v_cvt_pk_bf16_f32 v4, v100, v101
	v_add_f32_e32 v0, v102, v0
	v_cvt_pk_bf16_f32 v5, v102, v103
	v_add_f32_e32 v0, v103, v0
	v_sub_f32_e32 v104, v104, v240
	v_sub_f32_e32 v105, v105, v240
	v_exp_f32_e32 v104, v104
	s_waitcnt lgkmcnt(5)
	v_mfma_f32_32x32x16_bf16 v[80:95], v[248:251], v[180:183], v[80:95]
	ds_read2_b64 v[170:173], v239 offset0:4 offset1:6
	v_sub_f32_e32 v106, v106, v240
	v_exp_f32_e32 v105, v105
	v_sub_f32_e32 v107, v107, v240
	v_exp_f32_e32 v106, v106
	v_add_f32_e32 v0, v104, v0
	v_exp_f32_e32 v107, v107
	v_sub_f32_e32 v108, v108, v240
	s_waitcnt lgkmcnt(5)
	v_mfma_f32_32x32x16_bf16 v[80:95], v[252:255], v[176:179], v[80:95]
	ds_read2_b64 v[244:247], v238 offset0:4 offset1:6
	v_add_f32_e32 v0, v105, v0
	v_sub_f32_e32 v109, v109, v240
	v_exp_f32_e32 v108, v108
	v_cvt_pk_bf16_f32 v6, v104, v105
	v_add_f32_e32 v0, v106, v0
	v_exp_f32_e32 v109, v109
	v_sub_f32_e32 v110, v110, v240
	ds_read2_b64 v[248:251], v237 offset0:4 offset1:6
	ds_read2_b64 v[252:255], v235 offset0:4 offset1:6
	v_add_f32_e32 v0, v107, v0
	v_sub_f32_e32 v111, v111, v240
	v_exp_f32_e32 v110, v110
	v_cvt_pk_bf16_f32 v7, v106, v107
	v_exp_f32_e32 v111, v111
	v_add_f32_e32 v0, v108, v0
	v_add_f32_e32 v0, v109, v0
	v_cvt_pk_bf16_f32 v8, v108, v109
	v_add_f32_e32 v0, v110, v0
	v_cvt_pk_bf16_f32 v9, v110, v111
	v_add_f32_e32 v0, v111, v0
	v_max_f32_e32 v14, v81, v81
	v_max_f32_e32 v15, v80, v80
	v_max_f32_e32 v14, v15, v14
	v_max3_f32 v14, v14, v82, v83
	v_max3_f32 v14, v14, v84, v85
	v_max3_f32 v14, v14, v86, v87
	v_max3_f32 v14, v14, v88, v89
	v_max3_f32 v14, v14, v90, v91
	v_max3_f32 v14, v14, v92, v93
	v_max3_f32 v14, v14, v94, v95
	v_sub_f32_e32 v15, v14, v240
	v_cmp_lt_f32_e32 vcc, 4.0, v15
	s_cbranch_vccnz .Lf_rare1
; #define ATT_WV(n, x) asm volatile("s_waitcnt lgkmcnt(" #n ")" : "+v"(x) :: "memory")
; __device__ __forceinline__ void attn_phase(LAS unsigned char* ldsb, bf16_t* P, const bf16_t* Kn, const bf16_t* KPE, const bf16_t* VT) {
;     ...
;                     float ps = 0.f;
; #pragma unroll
;                     for (int kb = 0; kb < 2; ++kb)
; #pragma unroll
;                         for (int i = 0; i < 16; ++i) { const float p = __builtin_amdgcn_exp2f(st[kb][i] - mrun); st[kb][i] = p; ps += p; }
;                     lrun += ps;
;                     bf16x8 pb[2][2];
; #pragma unroll
;                     for (int kb = 0; kb < 2; ++kb)
; #pragma unroll
;                         for (int s2 = 0; s2 < 2; ++s2) {
;                             u32x4 pw; pw.x = pk2(st[kb][8 * s2 + 0], st[kb][8 * s2 + 1]); pw.y = pk2(st[kb][8 * s2 + 2], st[kb][8 * s2 + 3]);
;                             pw.z = pk2(st[kb][8 * s2 + 4], st[kb][8 * s2 + 5]); pw.w = pk2(st[kb][8 * s2 + 6], st[kb][8 * s2 + 7]);
;                             pb[kb][s2] = __builtin_bit_cast(bf16x8, pw); }
;                     {
;                         const unsigned va0 = (unsigned)(size_t)(sVt + r * 68 + 4 * hh), va1 = va0 + 32 * 68 * 2, va2 = va0 + 64 * 68 * 2, va3 = va0 + 96 * 68 * 2;
;                         bf16x8 vfa, vfb;
;     ...
;                         ATT_RV(vfa, va0, 0, 2);
;                         ATT_RV(vfb, va1, 0, 2); ATT_WV(1, vfa); o[0] = __builtin_amdgcn_mfma_f32_32x32x16_bf16(vfa, pb[0][0], o[0], 0, 0, 0);
;                         ATT_RV(vfa, va2, 0, 2); ATT_WV(1, vfb); o[1] = __builtin_amdgcn_mfma_f32_32x32x16_bf16(vfb, pb[0][0], o[1], 0, 0, 0);
;                         ATT_RV(vfb, va3, 0, 2); ATT_WV(1, vfa); o[2] = __builtin_amdgcn_mfma_f32_32x32x16_bf16(vfa, pb[0][0], o[2], 0, 0, 0);
;                         ATT_RV(vfa, va0, 4, 6); ATT_WV(1, vfb); o[3] = __builtin_amdgcn_mfma_f32_32x32x16_bf16(vfb, pb[0][0], o[3], 0, 0, 0);
;                         ATT_RV(vfb, va1, 4, 6); ATT_WV(1, vfa); o[0] = __builtin_amdgcn_mfma_f32_32x32x16_bf16(vfa, pb[0][1], o[0], 0, 0, 0);
;                         ATT_RV(vfa, va2, 4, 6); ATT_WV(1, vfb); o[1] = __builtin_amdgcn_mfma_f32_32x32x16_bf16(vfb, pb[0][1], o[1], 0, 0, 0);
;                         ATT_RV(vfb, va3, 4, 6); ATT_WV(1, vfa); o[2] = __builtin_amdgcn_mfma_f32_32x32x16_bf16(vfa, pb[0][1], o[2], 0, 0, 0);
.Lf_back1:
	s_waitcnt lgkmcnt(7)
	v_mfma_f32_32x32x16_bf16 v[64:79], v[154:157], v[2:5], v[64:79]
	ds_read2_b64 v[154:157], v239 offset0:8 offset1:10
	v_sub_f32_e32 v80, v80, v240
	v_sub_f32_e32 v81, v81, v240
	v_exp_f32_e32 v80, v80
	v_sub_f32_e32 v82, v82, v240
	v_exp_f32_e32 v81, v81
	s_waitcnt lgkmcnt(7)
	v_mfma_f32_32x32x16_bf16 v[48:63], v[158:161], v[2:5], v[48:63]
	ds_read2_b64 v[158:161], v238 offset0:8 offset1:10
	v_sub_f32_e32 v83, v83, v240
	v_exp_f32_e32 v82, v82
	v_add_f32_e32 v0, v80, v0
	v_exp_f32_e32 v83, v83
	v_sub_f32_e32 v84, v84, v240
	s_waitcnt lgkmcnt(7)
	v_mfma_f32_32x32x16_bf16 v[32:47], v[162:165], v[2:5], v[32:47]
	ds_read2_b64 v[162:165], v237 offset0:8 offset1:10
	v_add_f32_e32 v0, v81, v0
	v_sub_f32_e32 v85, v85, v240
	v_exp_f32_e32 v84, v84
	v_cvt_pk_bf16_f32 v10, v80, v81
	v_add_f32_e32 v0, v82, v0
	s_waitcnt lgkmcnt(7)
	v_mfma_f32_32x32x16_bf16 v[16:31], v[166:169], v[2:5], v[16:31]
	ds_read2_b64 v[166:169], v235 offset0:8 offset1:10
	v_exp_f32_e32 v85, v85
	v_sub_f32_e32 v86, v86, v240
	v_add_f32_e32 v0, v83, v0
	v_sub_f32_e32 v87, v87, v240
	v_exp_f32_e32 v86, v86
	s_waitcnt lgkmcnt(7)
	v_mfma_f32_32x32x16_bf16 v[64:79], v[170:173], v[6:9], v[64:79]
	ds_read2_b64 v[170:173], v239 offset0:12 offset1:14
	v_cvt_pk_bf16_f32 v11, v82, v83
	v_exp_f32_e32 v87, v87
	v_add_f32_e32 v0, v84, v0
	v_add_f32_e32 v0, v85, v0
	s_waitcnt lgkmcnt(7)
	v_mfma_f32_32x32x16_bf16 v[48:63], v[244:247], v[6:9], v[48:63]
	ds_read2_b64 v[244:247], v238 offset0:12 offset1:14
	v_cvt_pk_bf16_f32 v12, v84, v85
	v_add_f32_e32 v0, v86, v0
	v_cvt_pk_bf16_f32 v13, v86, v87
	v_add_f32_e32 v0, v87, v0
	s_waitcnt lgkmcnt(7)
	v_mfma_f32_32x32x16_bf16 v[32:47], v[248:251], v[6:9], v[32:47]
	ds_read2_b64 v[248:251], v237 offset0:12 offset1:14
	v_sub_f32_e32 v88, v88, v240
	v_sub_f32_e32 v89, v89, v240
	v_exp_f32_e32 v88, v88
	v_sub_f32_e32 v90, v90, v240
	v_exp_f32_e32 v89, v89
	v_sub_f32_e32 v91, v91, v240
	s_waitcnt lgkmcnt(7)
	v_mfma_f32_32x32x16_bf16 v[16:31], v[252:255], v[6:9], v[16:31]
	ds_read2_b64 v[252:255], v235 offset0:12 offset1:14
	v_exp_f32_e32 v90, v90
	v_add_f32_e32 v0, v88, v0
	v_exp_f32_e32 v91, v91
	v_sub_f32_e32 v92, v92, v240
	v_add_f32_e32 v0, v89, v0
	v_sub_f32_e32 v93, v93, v240
	s_waitcnt lgkmcnt(7)
	v_mfma_f32_32x32x16_bf16 v[64:79], v[154:157], v[10:13], v[64:79]
	v_exp_f32_e32 v92, v92
	v_cvt_pk_bf16_f32 v96, v88, v89
	v_add_f32_e32 v0, v90, v0
	v_exp_f32_e32 v93, v93
	v_sub_f32_e32 v94, v94, v240
	v_add_f32_e32 v0, v91, v0
	s_waitcnt lgkmcnt(6)
	v_mfma_f32_32x32x16_bf16 v[48:63], v[158:161], v[10:13], v[48:63]
	v_sub_f32_e32 v95, v95, v240
	v_exp_f32_e32 v94, v94
	v_cvt_pk_bf16_f32 v97, v90, v91
	v_exp_f32_e32 v95, v95
	v_add_f32_e32 v0, v92, v0
	s_waitcnt lgkmcnt(5)
	v_mfma_f32_32x32x16_bf16 v[32:47], v[162:165], v[10:13], v[32:47]
	v_add_f32_e32 v0, v93, v0
	v_cvt_pk_bf16_f32 v98, v92, v93
	v_add_f32_e32 v0, v94, v0
	v_cvt_pk_bf16_f32 v99, v94, v95
	v_add_f32_e32 v0, v95, v0
	s_waitcnt lgkmcnt(4)
	v_mfma_f32_32x32x16_bf16 v[16:31], v[166:169], v[10:13], v[16:31]
	s_waitcnt lgkmcnt(3)
	v_mfma_f32_32x32x16_bf16 v[64:79], v[170:173], v[96:99], v[64:79]
	v_add_f32_e32 v236, v236, v0
	s_waitcnt lgkmcnt(2)
	v_mfma_f32_32x32x16_bf16 v[48:63], v[244:247], v[96:99], v[48:63]
	s_waitcnt lgkmcnt(1)
	v_mfma_f32_32x32x16_bf16 v[32:47], v[248:251], v[96:99], v[32:47]
	s_waitcnt lgkmcnt(0)
	v_mfma_f32_32x32x16_bf16 v[16:31], v[252:255], v[96:99], v[16:31]
	s_branch .LBB0_1526
; __device__ __forceinline__ void attn_phase(LAS unsigned char* ldsb, bf16_t* P, const bf16_t* Kn, const bf16_t* KPE, const bf16_t* VT) {
;     ...
;                     mx = fmaxf(mx, __shfl_xor(mx, 32));
;                     if (__builtin_amdgcn_ballot_w64(mx > mrun) != 0ull) {
;                         const float mnew = fmaxf(mrun, mx);
;                         const float alpha = __builtin_amdgcn_exp2f(mrun - mnew);
;                         mrun = mnew; lrun *= alpha;
; #pragma unroll
;                         for (int d = 0; d < 4; ++d)
; #pragma unroll
;                             for (int i = 0; i < 16; ++i) o[d][i] *= alpha;
;                     }
.Lf_rare0:
	v_and_b32_e32 v10, 64, v234
	v_xor_b32_e32 v15, 32, v234
	v_add_u32_e32 v10, 64, v10
	v_cmp_lt_i32_e32 vcc, v15, v10
	s_nop 1
	v_cndmask_b32_e32 v15, v234, v15, vcc
	v_lshlrev_b32_e32 v15, 2, v15
	ds_bpermute_b32 v15, v15, v14
	s_waitcnt lgkmcnt(0)
	v_max_f32_e32 v15, v15, v15
	v_max_f32_e32 v14, v14, v15
	v_max_f32_e32 v15, v240, v240
	v_max_f32_e32 v15, v15, v14
	v_sub_f32_e32 v14, v240, v15
	v_exp_f32_e32 v14, v14
	v_mov_b32_e32 v240, v15
	s_nop 0
	v_pk_mul_f32 v[78:79], v[78:79], v[14:15] op_sel_hi:[1,0]
	v_pk_mul_f32 v[76:77], v[76:77], v[14:15] op_sel_hi:[1,0]
	v_pk_mul_f32 v[74:75], v[74:75], v[14:15] op_sel_hi:[1,0]
	v_pk_mul_f32 v[72:73], v[72:73], v[14:15] op_sel_hi:[1,0]
	v_pk_mul_f32 v[70:71], v[70:71], v[14:15] op_sel_hi:[1,0]
	v_pk_mul_f32 v[68:69], v[68:69], v[14:15] op_sel_hi:[1,0]
	v_pk_mul_f32 v[66:67], v[66:67], v[14:15] op_sel_hi:[1,0]
	v_pk_mul_f32 v[64:65], v[64:65], v[14:15] op_sel_hi:[1,0]
	v_pk_mul_f32 v[62:63], v[62:63], v[14:15] op_sel_hi:[1,0]
	v_pk_mul_f32 v[60:61], v[60:61], v[14:15] op_sel_hi:[1,0]
	v_pk_mul_f32 v[58:59], v[58:59], v[14:15] op_sel_hi:[1,0]
	v_pk_mul_f32 v[56:57], v[56:57], v[14:15] op_sel_hi:[1,0]
	v_pk_mul_f32 v[54:55], v[54:55], v[14:15] op_sel_hi:[1,0]
	v_pk_mul_f32 v[52:53], v[52:53], v[14:15] op_sel_hi:[1,0]
	v_pk_mul_f32 v[50:51], v[50:51], v[14:15] op_sel_hi:[1,0]
	v_pk_mul_f32 v[48:49], v[48:49], v[14:15] op_sel_hi:[1,0]
	v_pk_mul_f32 v[46:47], v[46:47], v[14:15] op_sel_hi:[1,0]
	v_pk_mul_f32 v[44:45], v[44:45], v[14:15] op_sel_hi:[1,0]
	v_pk_mul_f32 v[42:43], v[42:43], v[14:15] op_sel_hi:[1,0]
	v_pk_mul_f32 v[40:41], v[40:41], v[14:15] op_sel_hi:[1,0]
	v_pk_mul_f32 v[38:39], v[38:39], v[14:15] op_sel_hi:[1,0]
	v_pk_mul_f32 v[36:37], v[36:37], v[14:15] op_sel_hi:[1,0]
	v_pk_mul_f32 v[34:35], v[34:35], v[14:15] op_sel_hi:[1,0]
	v_pk_mul_f32 v[32:33], v[32:33], v[14:15] op_sel_hi:[1,0]
	v_pk_mul_f32 v[30:31], v[30:31], v[14:15] op_sel_hi:[1,0]
	v_pk_mul_f32 v[28:29], v[28:29], v[14:15] op_sel_hi:[1,0]
	v_pk_mul_f32 v[26:27], v[26:27], v[14:15] op_sel_hi:[1,0]
	v_pk_mul_f32 v[24:25], v[24:25], v[14:15] op_sel_hi:[1,0]
	v_pk_mul_f32 v[22:23], v[22:23], v[14:15] op_sel_hi:[1,0]
	v_pk_mul_f32 v[20:21], v[20:21], v[14:15] op_sel_hi:[1,0]
	v_pk_mul_f32 v[18:19], v[18:19], v[14:15] op_sel_hi:[1,0]
	v_pk_mul_f32 v[16:17], v[16:17], v[14:15] op_sel_hi:[1,0]
	v_mul_f32_e32 v236, v236, v14
	s_branch .Lf_back0
.Lf_rare1:
	v_and_b32_e32 v10, 64, v234
	v_xor_b32_e32 v15, 32, v234
	v_add_u32_e32 v10, 64, v10
	v_cmp_lt_i32_e32 vcc, v15, v10
	s_nop 1
	v_cndmask_b32_e32 v15, v234, v15, vcc
	v_lshlrev_b32_e32 v15, 2, v15
	ds_bpermute_b32 v15, v15, v14
	s_waitcnt lgkmcnt(0)
	v_max_f32_e32 v15, v15, v15
	v_max_f32_e32 v14, v14, v15
	v_max_f32_e32 v15, v240, v240
	v_max_f32_e32 v15, v15, v14
	v_sub_f32_e32 v14, v240, v15
	v_exp_f32_e32 v14, v14
	v_mov_b32_e32 v240, v15
	s_nop 0
	v_pk_mul_f32 v[78:79], v[78:79], v[14:15] op_sel_hi:[1,0]
	v_pk_mul_f32 v[76:77], v[76:77], v[14:15] op_sel_hi:[1,0]
	v_pk_mul_f32 v[74:75], v[74:75], v[14:15] op_sel_hi:[1,0]
	v_pk_mul_f32 v[72:73], v[72:73], v[14:15] op_sel_hi:[1,0]
	v_pk_mul_f32 v[70:71], v[70:71], v[14:15] op_sel_hi:[1,0]
	v_pk_mul_f32 v[68:69], v[68:69], v[14:15] op_sel_hi:[1,0]
	v_pk_mul_f32 v[66:67], v[66:67], v[14:15] op_sel_hi:[1,0]
	v_pk_mul_f32 v[64:65], v[64:65], v[14:15] op_sel_hi:[1,0]
	v_pk_mul_f32 v[62:63], v[62:63], v[14:15] op_sel_hi:[1,0]
	v_pk_mul_f32 v[60:61], v[60:61], v[14:15] op_sel_hi:[1,0]
	v_pk_mul_f32 v[58:59], v[58:59], v[14:15] op_sel_hi:[1,0]
	v_pk_mul_f32 v[56:57], v[56:57], v[14:15] op_sel_hi:[1,0]
	v_pk_mul_f32 v[54:55], v[54:55], v[14:15] op_sel_hi:[1,0]
	v_pk_mul_f32 v[52:53], v[52:53], v[14:15] op_sel_hi:[1,0]
	v_pk_mul_f32 v[50:51], v[50:51], v[14:15] op_sel_hi:[1,0]
	v_pk_mul_f32 v[48:49], v[48:49], v[14:15] op_sel_hi:[1,0]
	v_pk_mul_f32 v[46:47], v[46:47], v[14:15] op_sel_hi:[1,0]
	v_pk_mul_f32 v[44:45], v[44:45], v[14:15] op_sel_hi:[1,0]
	v_pk_mul_f32 v[42:43], v[42:43], v[14:15] op_sel_hi:[1,0]
	v_pk_mul_f32 v[40:41], v[40:41], v[14:15] op_sel_hi:[1,0]
	v_pk_mul_f32 v[38:39], v[38:39], v[14:15] op_sel_hi:[1,0]
	v_pk_mul_f32 v[36:37], v[36:37], v[14:15] op_sel_hi:[1,0]
	v_pk_mul_f32 v[34:35], v[34:35], v[14:15] op_sel_hi:[1,0]
	v_pk_mul_f32 v[32:33], v[32:33], v[14:15] op_sel_hi:[1,0]
	v_pk_mul_f32 v[30:31], v[30:31], v[14:15] op_sel_hi:[1,0]
	v_pk_mul_f32 v[28:29], v[28:29], v[14:15] op_sel_hi:[1,0]
	v_pk_mul_f32 v[26:27], v[26:27], v[14:15] op_sel_hi:[1,0]
	v_pk_mul_f32 v[24:25], v[24:25], v[14:15] op_sel_hi:[1,0]
	v_pk_mul_f32 v[22:23], v[22:23], v[14:15] op_sel_hi:[1,0]
	v_pk_mul_f32 v[20:21], v[20:21], v[14:15] op_sel_hi:[1,0]
	v_pk_mul_f32 v[18:19], v[18:19], v[14:15] op_sel_hi:[1,0]
	v_pk_mul_f32 v[16:17], v[16:17], v[14:15] op_sel_hi:[1,0]
	v_mul_f32_e32 v236, v236, v14
	v_mul_f32_e32 v0, v0, v14
	v_mul_f32_e32 v96, v96, v14
	v_mul_f32_e32 v97, v97, v14
	v_mul_f32_e32 v98, v98, v14
	v_mul_f32_e32 v99, v99, v14
	v_mul_f32_e32 v100, v100, v14
	v_mul_f32_e32 v101, v101, v14
	v_mul_f32_e32 v102, v102, v14
	v_mul_f32_e32 v103, v103, v14
	v_mul_f32_e32 v104, v104, v14
	v_mul_f32_e32 v105, v105, v14
	v_mul_f32_e32 v106, v106, v14
	v_mul_f32_e32 v107, v107, v14
	v_mul_f32_e32 v108, v108, v14
	v_mul_f32_e32 v109, v109, v14
	v_mul_f32_e32 v110, v110, v14
	v_mul_f32_e32 v111, v111, v14
	v_cvt_pk_bf16_f32 v2, v96, v97
	v_cvt_pk_bf16_f32 v3, v98, v99
	v_cvt_pk_bf16_f32 v4, v100, v101
	v_cvt_pk_bf16_f32 v5, v102, v103
	v_cvt_pk_bf16_f32 v6, v104, v105
	v_cvt_pk_bf16_f32 v7, v106, v107
	v_cvt_pk_bf16_f32 v8, v108, v109
	v_cvt_pk_bf16_f32 v9, v110, v111
	s_nop 1
	s_branch .Lf_back1
